# attention item: Q tile loads issued at item start, LDS writes after one wait (was 4 dependent load-wait-write rounds)
# speedup vs baseline: 1.1451x; 1.0022x over previous
.LBB0_189:
	v_cndmask_b32_e64 v0, 0, 1, s[0:1]
	v_readlane_b32 s4, v252, 57
	s_andn2_b64 vcc, exec, s[0:1]
	s_and_b32 s18, s3, 7
	s_lshl_b32 s100, s18, 7
	s_add_u32 s100, s92, s100
	s_addc_u32 s101, s93, 0
	v_lshlrev_b32_e32 v100, 3, v175
	v_and_b32_e32 v100, 56, v100
	v_lshlrev_b32_e32 v100, 1, v100
	v_ashrrev_i32_e32 v101, 3, v175
	v_add_u32_e32 v101, s11, v101
	v_mul_u32_u24_e32 v101, 0x1200, v101
	v_add_u32_e32 v101, v101, v100
	global_load_dwordx4 v[40:43], v101, s[100:101]
	v_add_u32_e32 v101, 0x24000, v101
	global_load_dwordx4 v[44:47], v101, s[100:101]
	v_add_u32_e32 v101, 0x24000, v101
	global_load_dwordx4 v[48:51], v101, s[100:101]
	v_add_u32_e32 v101, 0x24000, v101
	global_load_dwordx4 v[52:55], v101, s[100:101]
	v_add_u32_e32 v101, 0x24000, v101
	global_load_dwordx4 v[56:59], v101, s[100:101]
	v_add_u32_e32 v101, 0x24000, v101
	global_load_dwordx4 v[60:63], v101, s[100:101]
	v_add_u32_e32 v101, 0x24000, v101
	global_load_dwordx4 v[64:67], v101, s[100:101]
	v_add_u32_e32 v101, 0x24000, v101
	global_load_dwordx4 v[68:71], v101, s[100:101]
	v_or_b32_e32 v4, s4, v0
	v_ashrrev_i32_e32 v5, 31, v4
	v_lshlrev_b64 v[4:5], 2, v[4:5]
	v_lshl_add_u64 v[4:5], s[94:95], 0, v[4:5]
	global_load_dword v74, v[4:5], off
	s_cbranch_vccnz .LBB0_199
	s_movk_i32 s0, 0x1d1
	v_cmp_gt_i32_e32 vcc, s0, v2
	s_and_saveexec_b64 s[0:1], vcc
	s_cbranch_execz .LBB0_198
	v_max_i32_e32 v0, 0xd1, v2
	v_sub_u32_e32 v0, v0, v2
	v_add_u32_e32 v0, 0xff, v0
	v_cmp_lt_u32_e32 vcc, s33, v0
	s_mov_b64 s[6:7], -1
	v_mov_b32_e32 v4, v2
	s_and_saveexec_b64 s[4:5], vcc
	s_cbranch_execz .LBB0_195
	v_readlane_b32 s6, v252, 58
	v_readlane_b32 s7, v252, 59
	s_or_b32 s3, s6, s18
	v_lshrrev_b32_e32 v0, 8, v0
	s_mul_i32 s6, s7, 0x744
	s_mul_hi_u32 s7, s3, 0x744
	v_readlane_b32 s56, v251, 46
	v_add_u32_e32 v0, 1, v0
	s_add_i32 s7, s7, s6
	s_mulk_i32 s3, 0x744
	v_readlane_b32 s62, v251, 52
	v_readlane_b32 s63, v251, 53
	s_add_u32 s6, s62, s3
	v_and_b32_e32 v6, 0x1fffffe, v0
	v_add_u32_e32 v3, 0x100, v2
	v_readlane_b32 s3, v252, 0
	s_addc_u32 s7, s63, s7
	s_waitcnt vmcnt(0)
	v_mov_b32_e32 v75, v74
	v_lshl_add_u32 v7, v2, 2, s3
	s_mov_b64 s[8:9], 0
	v_mov_b32_e32 v8, v6
	v_mov_b64_e32 v[4:5], v[2:3]
	v_readlane_b32 s57, v251, 47
	v_readlane_b32 s58, v251, 48
	v_readlane_b32 s59, v251, 49
	v_readlane_b32 s60, v251, 50
	v_readlane_b32 s61, v251, 51
	v_readlane_b32 s64, v251, 54
	v_readlane_b32 s65, v251, 55
	v_readlane_b32 s66, v251, 56
	v_readlane_b32 s67, v251, 57
	v_readlane_b32 s68, v251, 58
	v_readlane_b32 s69, v251, 59
	v_readlane_b32 s70, v251, 60
	v_readlane_b32 s71, v251, 61

.LBB0_202:
	v_and_b32_e32 v5, 64, v207
	v_add_u32_e32 v180, 64, v5
	v_ashrrev_i32_e32 v4, 3, v175
	v_lshrrev_b32_e32 v32, 1, v4
	v_bitop3_b32 v0, v32, 7, v175 bitop3:0x48
	v_lshlrev_b32_e32 v0, 4, v0
	v_lshl_or_b32 v0, v4, 7, v0
	v_add_u32_e32 v3, s18, v0
	s_waitcnt vmcnt(0)
	ds_write_b128 v3, v[40:43]
	ds_write_b128 v3, v[44:47] offset:4096
	ds_write_b128 v3, v[48:51] offset:8192
	ds_write_b128 v3, v[52:55] offset:12288
	ds_write_b128 v3, v[56:59] offset:16384
	ds_write_b128 v3, v[60:63] offset:20480
	ds_write_b128 v3, v[64:67] offset:24576
	ds_write_b128 v3, v[68:71] offset:28672
	s_cmp_lt_i32 s13, 1
	s_mov_b64 s[6:7], -1
	s_waitcnt lgkmcnt(0)
	s_barrier
	s_cbranch_scc0 .LBB0_205
	s_lshl_b32 s0, s15, 8
	s_lshl_b32 s1, s13, 6
	s_sub_i32 s0, s0, s1
	s_addk_i32 s0, 0x4000
	s_mov_b64 s[6:7], 0
